# P6: rows re-dealt so every workgroup takes 32 prompt rows + 2 sample rows (sample rows no longer pile on 15 workgroups)
# speedup vs baseline: 1.0169x; 1.0169x over previous
.LBB0_1413:
	s_or_b64 exec, exec, s[0:1]
	v_readlane_b32 s0, v254, 56
	v_readlane_b32 s1, v254, 57
	v_mov_b32_e32 v96, v250
	s_and_b64 vcc, exec, s[0:1]
	s_waitcnt lgkmcnt(0)
	s_barrier
	s_cbranch_vccz .LBB0_1438
	s_mov_b32 s98, 0
	v_readlane_b32 s99, v254, 54
	s_nop 0
	s_cmpk_eq_u32 s99, 0x100
	s_cbranch_scc0 .Lp6_norebal
	v_readlane_b32 s99, v254, 50
	s_nop 0
	s_lshl_b32 s94, s99, 5
	s_add_i32 s69, s94, 32
	s_lshl_b32 s98, s99, 1
	s_addk_i32 s98, 0x2000
.Lp6_norebal:
	v_readlane_b32 s52, v254, 2
	v_readlane_b32 s53, v254, 3
	v_max_i32_e32 v0, 0x600, v96
	v_readlane_b32 s54, v254, 4
	v_readlane_b32 s55, v254, 5
	s_mov_b64 s[4:5], s[52:53]
	v_lshlrev_b32_e32 v103, 2, v96
	v_sub_u32_e32 v0, v0, v96
	s_mov_b64 s[6:7], s[54:55]
	v_and_b32_e32 v98, 0xfc, v103
	v_add_u32_e32 v0, 0x1ff, v0
	s_add_u32 s20, s6, 0x2000
	v_lshlrev_b32_e32 v100, 2, v98
	v_mov_b32_e32 v101, 0
	v_or_b32_e32 v108, 0x400, v98
	v_lshrrev_b32_e32 v1, 9, v0
	s_addc_u32 s21, s7, 0
	s_movk_i32 s0, 0x800
	v_add_u32_e32 v105, 32, v100
	v_or_b32_e32 v110, 0x500, v98
	v_lshl_add_u64 v[116:117], s[36:37], 0, v[100:101]
	v_lshlrev_b32_e32 v100, 2, v108
	v_add_u32_e32 v2, 1, v1
	v_add_u32_e32 v1, -1, v1
	s_add_u32 s2, s50, 0x4780000
	v_cmp_gt_i32_e64 s[4:5], s0, v96
	v_or_b32_e32 v112, 0x600, v98
	v_lshl_add_u64 v[118:119], s[36:37], 0, v[100:101]
	v_lshlrev_b32_e32 v100, 2, v110
	s_movk_i32 s0, 0x1ff
	v_lshrrev_b32_e32 v3, 1, v1
	s_addc_u32 s19, s51, 0
	v_or_b32_e32 v114, 0x700, v98
	v_lshl_add_u64 v[120:121], s[36:37], 0, v[100:101]
	v_lshlrev_b32_e32 v100, 2, v112
	v_add_u32_e32 v3, 1, v3
	v_cmp_lt_u32_e64 s[6:7], s0, v0
	v_and_b32_e32 v0, 0xfffffe, v2
	v_readlane_b32 s57, v254, 7
	v_readlane_b32 s60, v254, 10
	v_readlane_b32 s61, v254, 11
	v_readlane_b32 s62, v254, 12
	v_readlane_b32 s63, v254, 13
	v_readlane_b32 s64, v254, 14
	v_readlane_b32 s65, v254, 15
	v_lshl_add_u64 v[122:123], s[36:37], 0, v[100:101]
	v_lshlrev_b32_e32 v100, 2, v114
	v_lshl_add_u32 v107, v0, 9, v96
	v_and_b32_e32 v109, 3, v3
	v_cmp_ne_u32_e64 s[12:13], v2, v0
	s_add_u32 s25, s50, 0x47ec000
	v_and_b32_e32 v0, 63, v96
	v_readlane_b32 s56, v254, 6
	v_readlane_b32 s58, v254, 8
	v_readlane_b32 s59, v254, 9
	v_readlane_b32 s66, v254, 16
	v_readlane_b32 s67, v254, 17
	v_ashrrev_i32_e32 v99, 6, v96
	v_or_b32_e32 v102, 0x100, v98
	v_or_b32_e32 v104, 0x200, v98
	v_or_b32_e32 v106, 0x300, v98
	v_lshl_add_u64 v[124:125], s[36:37], 0, v[100:101]
	v_add_u32_e32 v97, 0x200, v96
	v_cmp_lt_u32_e64 s[8:9], 5, v1
	v_and_b32_e32 v111, -4, v3
	v_cmp_ne_u32_e64 s[10:11], 0, v109
	v_add_u32_e32 v113, 32, v103
	s_addc_u32 s33, s51, 0
	v_lshlrev_b32_e32 v126, 3, v0
	v_lshlrev_b32_e32 v128, 4, v0
	s_movk_i32 s57, 0x2000
	s_mov_b64 s[22:23], 0x800
	s_movk_i32 s60, 0x5ff
	s_mov_b32 s61, 0x2094d000
	s_mov_b32 s62, 0x2094e000
	v_mov_b32_e32 v115, 0x358637bd
	s_mov_b32 s63, 0x800000
	s_mov_b32 s64, 0x495d000
	s_mov_b32 s65, 0x495e000
	s_mov_b64 s[26:27], 0x8000
	s_mov_b64 s[28:29], 0x10000
	s_branch .LBB0_1416
.LBB0_1415:
	s_or_b64 exec, exec, s[0:1]
	s_cmp_ge_i32 s66, s69
	s_mov_b32 s94, s44
	s_cbranch_scc0 .LBB0_1416
	s_cmp_eq_u32 s98, 0
	s_cbranch_scc1 .LBB0_1438
	s_mov_b32 s94, s98
	s_add_i32 s69, s98, 2
	s_mov_b32 s98, 0
